# P0: non-temporal (nt) policy on the once-read f32 weight and x loads of the transpose / rmsnorm loops
# speedup vs baseline: 1.0159x; 1.0159x over previous
; template <bool MAP0> __device__ __forceinline__ void transpose_item(const float* W, int K, int N, bf16* WT, int item, int lane, const float* kscale) {
;     const int nblk = N / 32, kb = item / nblk, nb = item % nblk, kq = lane & 7, c4 = lane >> 3;
;     const int k0 = 64 * kb + 8 * kq, n0 = 32 * nb + 4 * c4;
;     f32x4 v[8];
; #pragma unroll
;     for (int i = 0; i < 8; ++i) v[i] = *(const f32x4*)(W + (size_t)(k0 + i) * N + n0);
;     if (kscale) {
;         const f32x4 g0 = *(const f32x4*)(kscale + k0), g1 = *(const f32x4*)(kscale + k0 + 4);
; #pragma unroll
;         for (int i = 0; i < 4; ++i) { v[i] = v[i] * g0[i]; v[4 + i] = v[4 + i] * g1[i]; }
;     }
; __device__ __forceinline__ void phase0(const PT& p, LAS unsigned char* lds, int tid, int lane, int wave) {
;     ...
;     for (int it = gw; it < I0 + I1 + I2 + I3; it += NGW) {
;         int r = it;
;         if (r < I0) { transpose_item<true>(p.in[2], 2048, N0R, (bf16*)(ws + WS_W0IN), r, lane, nullptr); continue; } r -= I0;
;         if (r < I1) { transpose_item<false>(p.in[13], 4096, 2048, (bf16*)(ws + WS_W0OUT), r, lane, nullptr); continue; } r -= I1;
;         if (r < I2) { transpose_item<false>(p.in[15], 2048, 8192, (bf16*)(ws + WS_W1IN), r, lane, p.in[14]); continue; } r -= I2;
;         transpose_item<false>(p.in[21], 2048, 2048, (bf16*)(ws + WS_W1OUT), r, lane, nullptr);
.LBB0_18:
	s_cmpk_gt_i32 s33, 0x2c1f
	s_mov_b64 s[0:1], -1
	s_cbranch_scc0 .LBB0_30
	s_cmpk_gt_u32 s33, 0x3c1f
	s_cbranch_scc0 .LBB0_27
	s_cmpk_gt_u32 s33, 0x5c1f
	s_cbranch_scc0 .LBB0_22
	ds_read_b64 v[2:3], v40
	s_add_i32 s34, s33, 0xa3e0
	s_and_b32 s0, s34, 0xffc0
	s_lshl_b32 s34, s34, 5
	s_and_b32 s34, s34, 0x7e0
	v_or_b32_e32 v50, s34, v39
	v_or_b32_e32 v45, s0, v35
	s_waitcnt lgkmcnt(0)
	v_readfirstlane_b32 s1, v3
	v_readfirstlane_b32 s0, v2
	v_lshlrev_b32_e32 v36, 2, v50
	s_nop 0
	v_lshl_add_u64 v[2:3], s[0:1], 0, v[36:37]
	v_lshlrev_b32_e32 v36, 13, v45
	v_lshl_add_u64 v[26:27], v[2:3], 0, v[36:37]
	v_add_co_u32_e32 v10, vcc, s20, v26
	v_lshlrev_b32_e32 v36, 1, v45
	s_nop 0
	v_addc_co_u32_e32 v11, vcc, 0, v27, vcc
	v_add_co_u32_e32 v18, vcc, s21, v26
	global_load_dwordx4 v[2:5], v[26:27], off nt
	global_load_dwordx4 v[6:9], v[10:11], off nt
	v_addc_co_u32_e32 v19, vcc, 0, v27, vcc
	v_add_co_u32_e32 v20, vcc, s22, v26
	s_mov_b64 s[0:1], 0
	s_nop 0
	v_addc_co_u32_e32 v21, vcc, 0, v27, vcc
	v_add_co_u32_e32 v28, vcc, s23, v26
	global_load_dwordx4 v[10:13], v[18:19], off nt
	global_load_dwordx4 v[14:17], v[20:21], off nt
	v_addc_co_u32_e32 v29, vcc, 0, v27, vcc
	v_add_co_u32_e32 v30, vcc, s24, v26
	s_waitcnt vmcnt(2)
	v_cvt_pk_bf16_f32 v54, v4, v8
	v_addc_co_u32_e32 v31, vcc, 0, v27, vcc
	v_add_co_u32_e32 v46, vcc, s25, v26
	global_load_dwordx4 v[18:21], v[28:29], off nt
	global_load_dwordx4 v[22:25], v[30:31], off nt
	v_addc_co_u32_e32 v47, vcc, 0, v27, vcc
	v_add_co_u32_e32 v48, vcc, s26, v26
	s_waitcnt vmcnt(2)
	v_cvt_pk_bf16_f32 v51, v11, v15
	v_addc_co_u32_e32 v49, vcc, 0, v27, vcc
	global_load_dwordx4 v[26:29], v[46:47], off nt
	global_load_dwordx4 v[30:33], v[48:49], off nt
	v_lshl_add_u64 v[46:47], s[8:9], 0, v[36:37]
	v_lshlrev_b32_e32 v36, 12, v50
	v_lshl_add_u64 v[58:59], v[46:47], 0, v[36:37]
	v_add_co_u32_e32 v60, vcc, s20, v58
	v_cvt_pk_bf16_f32 v46, v2, v6
	s_nop 0
	v_addc_co_u32_e32 v61, vcc, 0, v59, vcc
	v_add_co_u32_e32 v62, vcc, 0x3000, v58
	v_cvt_pk_bf16_f32 v47, v10, v14
	s_nop 0
	v_addc_co_u32_e32 v63, vcc, 0, v59, vcc
	v_cvt_pk_bf16_f32 v50, v3, v7
	v_cvt_pk_bf16_f32 v55, v12, v16
	v_cvt_pk_bf16_f32 v2, v5, v9
	v_cvt_pk_bf16_f32 v3, v13, v17
	s_waitcnt vmcnt(2)
	v_cvt_pk_bf16_f32 v48, v18, v22
	v_cvt_pk_bf16_f32 v52, v19, v23
	v_cvt_pk_bf16_f32 v56, v20, v24
	v_cvt_pk_bf16_f32 v4, v21, v25
	s_waitcnt vmcnt(0)
	v_cvt_pk_bf16_f32 v49, v26, v30
	v_cvt_pk_bf16_f32 v53, v27, v31
	v_cvt_pk_bf16_f32 v57, v28, v32
	v_cvt_pk_bf16_f32 v5, v29, v33
	global_store_dwordx4 v[58:59], v[46:49], off
	global_store_dwordx4 v[60:61], v[50:53], off offset:-4096
	global_store_dwordx4 v[60:61], v[54:57], off
	global_store_dwordx4 v[62:63], v[2:5], off
.LBB0_22:
	s_andn2_b64 vcc, exec, s[0:1]
	s_cbranch_vccnz .LBB0_26
	ds_read_b64 v[2:3], v41
	s_add_i32 s34, s33, 0xc3e0
	s_bfe_u32 s0, s34, 0x80008
	s_lshl_b32 s34, s34, 5
	s_and_b32 s34, s34, 0x1fe0
	v_or_b32_e32 v45, s34, v39
	v_lshl_or_b32 v46, s0, 6, v35
	s_waitcnt lgkmcnt(0)
	v_readfirstlane_b32 s1, v3
	v_readfirstlane_b32 s0, v2
	v_lshlrev_b32_e32 v36, 2, v45
	s_nop 0
	v_lshl_add_u64 v[2:3], s[0:1], 0, v[36:37]
	v_lshlrev_b32_e32 v36, 15, v46
	v_lshl_add_u64 v[26:27], v[2:3], 0, v[36:37]
	v_add_co_u32_e32 v10, vcc, s23, v26
	s_nop 1
	v_addc_co_u32_e32 v11, vcc, 0, v27, vcc
	v_add_co_u32_e32 v18, vcc, s27, v26
	global_load_dwordx4 v[2:5], v[26:27], off nt
	global_load_dwordx4 v[6:9], v[10:11], off nt
	v_addc_co_u32_e32 v19, vcc, 0, v27, vcc
	v_add_co_u32_e32 v20, vcc, s28, v26
	s_nop 1
	v_addc_co_u32_e32 v21, vcc, 0, v27, vcc
	v_add_co_u32_e32 v28, vcc, s29, v26
	global_load_dwordx4 v[10:13], v[18:19], off nt
	global_load_dwordx4 v[14:17], v[20:21], off nt
	v_addc_co_u32_e32 v29, vcc, 0, v27, vcc
	v_add_co_u32_e32 v30, vcc, 0x28000, v26
	s_nop 1
	v_addc_co_u32_e32 v31, vcc, 0, v27, vcc
	v_add_co_u32_e32 v48, vcc, 0x30000, v26
	global_load_dwordx4 v[18:21], v[28:29], off nt
	global_load_dwordx4 v[22:25], v[30:31], off nt
	v_addc_co_u32_e32 v49, vcc, 0, v27, vcc
	v_add_co_u32_e32 v50, vcc, 0x38000, v26
	s_nop 1
	v_addc_co_u32_e32 v51, vcc, 0, v27, vcc
	global_load_dwordx4 v[26:29], v[48:49], off nt
	global_load_dwordx4 v[30:33], v[50:51], off nt
	ds_read_b64 v[48:49], v42
	s_waitcnt lgkmcnt(0)
	v_readfirstlane_b32 s1, v49
	v_readfirstlane_b32 s0, v48
	s_cmp_eq_u64 s[0:1], 0
	s_cbranch_scc1 .LBB0_25
	v_lshlrev_b32_e32 v36, 2, v46
	s_nop 1
	global_load_dwordx4 v[48:51], v36, s[0:1] nt
	global_load_dwordx4 v[52:55], v36, s[0:1] offset:16 nt
	s_waitcnt vmcnt(1)
	v_pk_mul_f32 v[4:5], v[4:5], v[48:49] op_sel_hi:[1,0]
	v_pk_mul_f32 v[2:3], v[2:3], v[48:49] op_sel_hi:[1,0]
	v_pk_mul_f32 v[8:9], v[8:9], v[48:49] op_sel:[0,1]
	v_pk_mul_f32 v[6:7], v[6:7], v[48:49] op_sel:[0,1]
	v_mov_b32_e32 v36, v51
	s_waitcnt vmcnt(0)
	v_mov_b32_e32 v48, v55
	v_pk_mul_f32 v[20:21], v[20:21], v[52:53] op_sel_hi:[1,0]
	v_pk_mul_f32 v[18:19], v[18:19], v[52:53] op_sel_hi:[1,0]
	v_pk_mul_f32 v[24:25], v[24:25], v[52:53] op_sel:[0,1]
	v_pk_mul_f32 v[22:23], v[22:23], v[52:53] op_sel:[0,1]
	v_pk_mul_f32 v[12:13], v[12:13], v[50:51] op_sel_hi:[1,0]
	v_pk_mul_f32 v[10:11], v[10:11], v[50:51] op_sel_hi:[1,0]
	v_pk_mul_f32 v[28:29], v[28:29], v[54:55] op_sel_hi:[1,0]
	v_pk_mul_f32 v[26:27], v[26:27], v[54:55] op_sel_hi:[1,0]
	v_pk_mul_f32 v[16:17], v[16:17], v[36:37] op_sel_hi:[1,0]
	v_pk_mul_f32 v[14:15], v[14:15], v[36:37] op_sel_hi:[1,0]
	v_pk_mul_f32 v[32:33], v[32:33], v[48:49] op_sel_hi:[1,0]
	v_pk_mul_f32 v[30:31], v[30:31], v[48:49] op_sel_hi:[1,0]

; template <bool MAP0> __device__ __forceinline__ void transpose_item(const float* W, int K, int N, bf16* WT, int item, int lane, const float* kscale) {
;     const int nblk = N / 32, kb = item / nblk, nb = item % nblk, kq = lane & 7, c4 = lane >> 3;
;     const int k0 = 64 * kb + 8 * kq, n0 = 32 * nb + 4 * c4;
;     f32x4 v[8];
; #pragma unroll
;     for (int i = 0; i < 8; ++i) v[i] = *(const f32x4*)(W + (size_t)(k0 + i) * N + n0);
;     ...
; #pragma unroll
;     for (int j = 0; j < 4; ++j) {
;         u32x4 o; o.x = pk2(v[0][j], v[1][j]); o.y = pk2(v[2][j], v[3][j]); o.z = pk2(v[4][j], v[5][j]); o.w = pk2(v[6][j], v[7][j]);
;         *(u32x4*)(WT + (size_t)((MAP0 ? w0in_row(n0) : n0) + j) * K + k0) = o;
;     }
; __device__ __forceinline__ void phase0(const PT& p, LAS unsigned char* lds, int tid, int lane, int wave) {
;     ...
;         if (r < I1) { transpose_item<false>(p.in[13], 4096, 2048, (bf16*)(ws + WS_W0OUT), r, lane, nullptr); continue; } r -= I1;
.LBB0_27:
	s_andn2_b64 vcc, exec, s[0:1]
	s_cbranch_vccnz .LBB0_29
	ds_read_b64 v[2:3], v43
	s_add_i32 s34, s33, 0xd3e0
	s_and_b32 s0, s34, 0xffc0
	s_lshl_b32 s34, s34, 5
	s_and_b32 s34, s34, 0x7e0
	v_or_b32_e32 v50, s34, v39
	v_or_b32_e32 v45, s0, v35
	s_waitcnt lgkmcnt(0)
	v_readfirstlane_b32 s1, v3
	v_readfirstlane_b32 s0, v2
	v_lshlrev_b32_e32 v36, 2, v50
	s_nop 0
	v_lshl_add_u64 v[2:3], s[0:1], 0, v[36:37]
	v_lshlrev_b32_e32 v36, 13, v45
	v_lshl_add_u64 v[26:27], v[2:3], 0, v[36:37]
	v_add_co_u32_e32 v10, vcc, s20, v26
	v_lshlrev_b32_e32 v36, 1, v45
	s_nop 0
	v_addc_co_u32_e32 v11, vcc, 0, v27, vcc
	v_add_co_u32_e32 v18, vcc, s21, v26
	global_load_dwordx4 v[2:5], v[26:27], off nt
	global_load_dwordx4 v[6:9], v[10:11], off nt
	v_addc_co_u32_e32 v19, vcc, 0, v27, vcc
	v_add_co_u32_e32 v20, vcc, s22, v26
	s_waitcnt vmcnt(0)
	v_cvt_pk_bf16_f32 v54, v4, v8
	v_addc_co_u32_e32 v21, vcc, 0, v27, vcc
	v_add_co_u32_e32 v28, vcc, s23, v26
	global_load_dwordx4 v[10:13], v[18:19], off nt
	global_load_dwordx4 v[14:17], v[20:21], off nt
	v_addc_co_u32_e32 v29, vcc, 0, v27, vcc
	v_add_co_u32_e32 v30, vcc, s24, v26
	s_waitcnt vmcnt(0)
	v_cvt_pk_bf16_f32 v51, v11, v15
	v_addc_co_u32_e32 v31, vcc, 0, v27, vcc
	v_add_co_u32_e32 v46, vcc, s25, v26
	global_load_dwordx4 v[18:21], v[28:29], off nt
	global_load_dwordx4 v[22:25], v[30:31], off nt
	v_addc_co_u32_e32 v47, vcc, 0, v27, vcc
	v_add_co_u32_e32 v48, vcc, s26, v26
	v_cvt_pk_bf16_f32 v55, v12, v16
	s_nop 0
	v_addc_co_u32_e32 v49, vcc, 0, v27, vcc
	global_load_dwordx4 v[26:29], v[46:47], off nt
	global_load_dwordx4 v[30:33], v[48:49], off nt
	v_lshl_add_u64 v[46:47], s[12:13], 0, v[36:37]
	v_lshlrev_b32_e32 v36, 13, v50
	v_lshl_add_u64 v[58:59], v[46:47], 0, v[36:37]
	v_add_co_u32_e32 v60, vcc, s20, v58
	v_cvt_pk_bf16_f32 v46, v2, v6
	s_nop 0
	v_addc_co_u32_e32 v61, vcc, 0, v59, vcc
	v_add_co_u32_e32 v62, vcc, s21, v58
	v_cvt_pk_bf16_f32 v47, v10, v14
	s_nop 0
	v_addc_co_u32_e32 v63, vcc, 0, v59, vcc
	v_add_co_u32_e32 v64, vcc, 0x6000, v58
	v_cvt_pk_bf16_f32 v50, v3, v7
	s_nop 0
	v_addc_co_u32_e32 v65, vcc, 0, v59, vcc
	v_cvt_pk_bf16_f32 v2, v5, v9
	v_cvt_pk_bf16_f32 v3, v13, v17
	s_waitcnt vmcnt(2)
	v_cvt_pk_bf16_f32 v48, v18, v22
	v_cvt_pk_bf16_f32 v52, v19, v23
	v_cvt_pk_bf16_f32 v56, v20, v24
	v_cvt_pk_bf16_f32 v4, v21, v25
	s_waitcnt vmcnt(0)
	v_cvt_pk_bf16_f32 v49, v26, v30
	v_cvt_pk_bf16_f32 v53, v27, v31
	v_cvt_pk_bf16_f32 v57, v28, v32
	v_cvt_pk_bf16_f32 v5, v29, v33
	global_store_dwordx4 v[58:59], v[46:49], off
	global_store_dwordx4 v[60:61], v[50:53], off
	global_store_dwordx4 v[62:63], v[54:57], off
	global_store_dwordx4 v[64:65], v[2:5], off

; template <bool MAP0> __device__ __forceinline__ void transpose_item(const float* W, int K, int N, bf16* WT, int item, int lane, const float* kscale) {
;     const int nblk = N / 32, kb = item / nblk, nb = item % nblk, kq = lane & 7, c4 = lane >> 3;
;     const int k0 = 64 * kb + 8 * kq, n0 = 32 * nb + 4 * c4;
;     f32x4 v[8];
; #pragma unroll
;     for (int i = 0; i < 8; ++i) v[i] = *(const f32x4*)(W + (size_t)(k0 + i) * N + n0);
;     ...
; #pragma unroll
;     for (int j = 0; j < 4; ++j) {
;         u32x4 o; o.x = pk2(v[0][j], v[1][j]); o.y = pk2(v[2][j], v[3][j]); o.z = pk2(v[4][j], v[5][j]); o.w = pk2(v[6][j], v[7][j]);
;         *(u32x4*)(WT + (size_t)((MAP0 ? w0in_row(n0) : n0) + j) * K + k0) = o;
;     }
; __device__ __forceinline__ void phase0(const PT& p, LAS unsigned char* lds, int tid, int lane, int wave) {
;     ...
;         if (r < I0) { transpose_item<true>(p.in[2], 2048, N0R, (bf16*)(ws + WS_W0IN), r, lane, nullptr); continue; } r -= I0;
.LBB0_30:
	s_andn2_b64 vcc, exec, s[0:1]
	s_cbranch_vccnz .LBB0_17
	ds_read_b64 v[2:3], v44
	s_mul_hi_i32 s0, s33, 0xb9a7862b
	s_add_i32 s0, s0, s33
	s_waitcnt lgkmcnt(0)
	v_readfirstlane_b32 s1, v3
	v_readfirstlane_b32 s34, v2
	s_nop 0
	v_mov_b32_e32 v3, s1
	s_lshr_b32 s1, s0, 31
	s_ashr_i32 s0, s0, 8
	v_mov_b32_e32 v2, s34
	s_add_i32 s34, s0, s1
	s_mul_i32 s0, s34, 0xffffd3e0
	s_add_i32 s35, s7, s0
	v_add_u32_e32 v48, s35, v39
	v_ashrrev_i32_e32 v49, 31, v48
	v_lshl_or_b32 v46, s34, 6, v35
	v_lshl_add_u64 v[26:27], v[48:49], 2, v[2:3]
	v_mad_i64_i32 v[10:11], s[0:1], v46, s30, v[26:27]
	v_or_b32_e32 v2, 1, v46
	v_mad_i64_i32 v[12:13], s[0:1], v2, s30, v[26:27]
	global_load_dwordx4 v[2:5], v[10:11], off nt
	global_load_dwordx4 v[6:9], v[12:13], off nt
	v_or_b32_e32 v10, 2, v46
	v_mad_i64_i32 v[18:19], s[0:1], v10, s30, v[26:27]
	v_or_b32_e32 v10, 3, v46
	v_mad_i64_i32 v[20:21], s[0:1], v10, s30, v[26:27]
	global_load_dwordx4 v[10:13], v[18:19], off nt
	global_load_dwordx4 v[14:17], v[20:21], off nt
	v_or_b32_e32 v18, 4, v46
	v_mad_i64_i32 v[28:29], s[0:1], v18, s30, v[26:27]
	v_or_b32_e32 v18, 5, v46
	v_mad_i64_i32 v[30:31], s[0:1], v18, s30, v[26:27]
	global_load_dwordx4 v[18:21], v[28:29], off nt
	global_load_dwordx4 v[22:25], v[30:31], off nt
	v_or_b32_e32 v28, 6, v46
	v_mad_i64_i32 v[50:51], s[0:1], v28, s30, v[26:27]
	v_or_b32_e32 v28, 7, v46
	v_mad_i64_i32 v[52:53], s[0:1], v28, s30, v[26:27]
	global_load_dwordx4 v[26:29], v[50:51], off nt
	global_load_dwordx4 v[30:33], v[52:53], off nt
	s_cmpk_lt_u32 s35, 0x1000
	s_mulk_i32 s34, 0xa7c0
	s_cselect_b64 vcc, -1, 0
	s_cmpk_lt_u32 s35, 0x1800
	s_cselect_b64 s[0:1], -1, 0
	s_add_i32 s34, s17, s34
	s_and_b32 s35, s34, 0x7fffff00
	v_ashrrev_i32_e32 v47, 31, v46
	v_and_b32_e32 v45, 0x7c, v48
	s_and_b32 s34, s34, 0xffffff00
	s_addk_i32 s35, 0xe080
	v_lshl_add_u64 v[58:59], v[46:47], 1, s[14:15]
	v_or_b32_e32 v46, s34, v45
	v_or_b32_e32 v45, s35, v45
	v_add_u32_e32 v36, 0x800, v48
	v_cndmask_b32_e64 v45, v48, v45, s[0:1]
	v_cndmask_b32_e32 v36, v45, v36, vcc
	v_cmp_gt_i32_e32 vcc, s31, v48
	s_waitcnt vmcnt(6)
	v_cvt_pk_bf16_f32 v54, v4, v8
	v_cndmask_b32_e32 v60, v36, v46, vcc
	v_or_b32_e32 v46, 1, v60
	v_ashrrev_i32_e32 v47, 31, v46
	v_ashrrev_i32_e32 v61, 31, v60
	v_lshlrev_b64 v[46:47], 12, v[46:47]
	v_or_b32_e32 v48, 2, v60
	v_lshlrev_b64 v[50:51], 12, v[60:61]
	v_lshl_add_u64 v[64:65], v[58:59], 0, v[46:47]
	v_cvt_pk_bf16_f32 v46, v2, v6
	v_or_b32_e32 v6, 3, v60
	v_ashrrev_i32_e32 v49, 31, v48
	v_lshl_add_u64 v[62:63], v[58:59], 0, v[50:51]
	v_cvt_pk_bf16_f32 v50, v3, v7
	v_ashrrev_i32_e32 v7, 31, v6
	v_lshlrev_b64 v[48:49], 12, v[48:49]
	v_lshlrev_b64 v[6:7], 12, v[6:7]
	v_lshl_add_u64 v[66:67], v[58:59], 0, v[48:49]
	s_waitcnt vmcnt(4)
	v_cvt_pk_bf16_f32 v47, v10, v14
	s_waitcnt vmcnt(2)
	v_cvt_pk_bf16_f32 v48, v18, v22
	v_cvt_pk_bf16_f32 v2, v5, v9
	s_waitcnt vmcnt(0)
	v_cvt_pk_bf16_f32 v49, v26, v30
	v_cvt_pk_bf16_f32 v3, v13, v17
	v_cvt_pk_bf16_f32 v4, v21, v25
	v_cvt_pk_bf16_f32 v5, v29, v33
	v_lshl_add_u64 v[6:7], v[58:59], 0, v[6:7]
	v_cvt_pk_bf16_f32 v51, v11, v15
	v_cvt_pk_bf16_f32 v52, v19, v23
	v_cvt_pk_bf16_f32 v53, v27, v31
	v_cvt_pk_bf16_f32 v55, v12, v16
	v_cvt_pk_bf16_f32 v56, v20, v24
	v_cvt_pk_bf16_f32 v57, v28, v32
	global_store_dwordx4 v[62:63], v[46:49], off
	global_store_dwordx4 v[64:65], v[50:53], off
	global_store_dwordx4 v[66:67], v[54:57], off
	global_store_dwordx4 v[6:7], v[2:5], off
	s_branch .LBB0_17

; __device__ __forceinline__ void phase0(const PT& p, LAS unsigned char* lds, int tid, int lane, int wave) {
;     ...
;     const float* g0 = p.in[1]; bf16* H0 = (bf16*)(ws + WS_H0);
;     for (int m = gw; m < M; m += NGW) {
;         const f32x4* xr = (const f32x4*)(p.in[0] + (size_t)m * 2048) + lane; f32x4 v[8]; float s = 0.f;
; #pragma unroll
;         for (int j = 0; j < 8; ++j) { v[j] = xr[64 * j]; s += (v[j].x * v[j].x + v[j].y * v[j].y) + (v[j].z * v[j].z + v[j].w * v[j].w); }
;         const float rs = rsqrtf(wave_sum(s) * (1.f / 2048.f) + EPS);
;         if (lane == 0) ((float*)(ws + WS_RS0))[m] = rs;
;         u32x2* o = (u32x2*)(H0 + (size_t)m * 2048) + lane;
; #pragma unroll
;         for (int j = 0; j < 8; ++j) { const f32x4 g = ((const f32x4*)g0)[lane + 64 * j]; u32x2 w; w.x = pk2(v[j].x * rs * g.x, v[j].y * rs * g.y); w.y = pk2(v[j].z * rs * g.z, v[j].w * rs * g.w); o[64 * j] = w; }
;     }
.LBB0_53:
	s_or_b64 exec, exec, s[14:15]
	global_load_dwordx4 v[58:61], v[36:37], off nt
	v_lshl_add_u64 v[62:63], s[4:5], 0, v[48:49]
	v_pk_mul_f32 v[30:31], v[30:31], v[34:35] op_sel_hi:[1,0]
	v_pk_mul_f32 v[32:33], v[32:33], v[34:35] op_sel_hi:[1,0]
	v_add_co_u32_e32 v62, vcc, s19, v62
	v_pk_mul_f32 v[26:27], v[26:27], v[34:35] op_sel_hi:[1,0]
	s_nop 0
	v_addc_co_u32_e32 v63, vcc, 0, v63, vcc
	v_pk_mul_f32 v[28:29], v[28:29], v[34:35] op_sel_hi:[1,0]
	v_pk_mul_f32 v[22:23], v[22:23], v[34:35] op_sel_hi:[1,0]
	v_pk_mul_f32 v[24:25], v[24:25], v[34:35] op_sel_hi:[1,0]
	v_pk_mul_f32 v[18:19], v[18:19], v[34:35] op_sel_hi:[1,0]
	v_pk_mul_f32 v[20:21], v[20:21], v[34:35] op_sel_hi:[1,0]
	v_pk_mul_f32 v[2:3], v[2:3], v[34:35] op_sel_hi:[1,0]
	v_pk_mul_f32 v[4:5], v[4:5], v[34:35] op_sel_hi:[1,0]
	v_pk_mul_f32 v[10:11], v[10:11], v[34:35] op_sel_hi:[1,0]
	v_pk_mul_f32 v[12:13], v[12:13], v[34:35] op_sel_hi:[1,0]
	s_add_i32 s6, s6, s80
	v_pk_mul_f32 v[6:7], v[6:7], v[34:35] op_sel_hi:[1,0]
	v_pk_mul_f32 v[8:9], v[8:9], v[34:35] op_sel_hi:[1,0]
	s_add_u32 s16, s16, s8
	s_addc_u32 s17, s17, s9
	v_lshl_add_u64 v[48:49], v[48:49], 0, s[10:11]
	s_cmpk_lt_i32 s6, 0x4000
	v_lshl_add_u64 v[50:51], v[50:51], 0, s[12:13]
	s_waitcnt vmcnt(0)
	v_pk_mul_f32 v[30:31], v[30:31], v[58:59]
	v_pk_mul_f32 v[32:33], v[32:33], v[60:61]
	v_cvt_pk_bf16_f32 v30, v30, v31
	v_cvt_pk_bf16_f32 v31, v32, v33
	global_store_dwordx2 v[62:63], v[30:31], off
	global_load_dwordx4 v[30:33], v[36:37], off offset:1024 nt
	s_waitcnt vmcnt(0)
	v_pk_mul_f32 v[26:27], v[26:27], v[30:31]
	v_pk_mul_f32 v[28:29], v[28:29], v[32:33]
	v_cvt_pk_bf16_f32 v26, v26, v27
	v_cvt_pk_bf16_f32 v27, v28, v29
	global_store_dwordx2 v[62:63], v[26:27], off offset:512
	global_load_dwordx4 v[26:29], v[36:37], off offset:2048 nt
	s_waitcnt vmcnt(0)
	v_pk_mul_f32 v[22:23], v[22:23], v[26:27]
	v_pk_mul_f32 v[24:25], v[24:25], v[28:29]
	v_cvt_pk_bf16_f32 v22, v22, v23
	v_cvt_pk_bf16_f32 v23, v24, v25
	global_store_dwordx2 v[62:63], v[22:23], off offset:1024
	global_load_dwordx4 v[22:25], v[36:37], off offset:3072 nt
	s_waitcnt vmcnt(0)
	v_pk_mul_f32 v[18:19], v[18:19], v[22:23]
	v_pk_mul_f32 v[20:21], v[20:21], v[24:25]
	v_cvt_pk_bf16_f32 v18, v18, v19
	v_cvt_pk_bf16_f32 v19, v20, v21
	global_store_dwordx2 v[62:63], v[18:19], off offset:1536
	global_load_dwordx4 v[18:21], v[38:39], off nt
	s_waitcnt vmcnt(0)
	v_pk_mul_f32 v[2:3], v[2:3], v[18:19]
	v_pk_mul_f32 v[4:5], v[4:5], v[20:21]
	v_cvt_pk_bf16_f32 v2, v2, v3
	v_cvt_pk_bf16_f32 v3, v4, v5
	global_store_dwordx2 v[62:63], v[2:3], off offset:2048
	global_load_dwordx4 v[2:5], v[40:41], off nt
	s_waitcnt vmcnt(0)
	v_pk_mul_f32 v[2:3], v[10:11], v[2:3]
	v_pk_mul_f32 v[4:5], v[12:13], v[4:5]
	v_cvt_pk_bf16_f32 v2, v2, v3
	v_cvt_pk_bf16_f32 v3, v4, v5
	global_store_dwordx2 v[62:63], v[2:3], off offset:2560
	global_load_dwordx4 v[2:5], v[42:43], off nt
	v_pk_mul_f32 v[10:11], v[14:15], v[34:35] op_sel_hi:[1,0]
	v_pk_mul_f32 v[12:13], v[16:17], v[34:35] op_sel_hi:[1,0]
	s_waitcnt vmcnt(0)
	v_pk_mul_f32 v[2:3], v[10:11], v[2:3]
	v_pk_mul_f32 v[4:5], v[12:13], v[4:5]
	v_cvt_pk_bf16_f32 v2, v2, v3
	v_cvt_pk_bf16_f32 v3, v4, v5
	global_store_dwordx2 v[62:63], v[2:3], off offset:3072
	global_load_dwordx4 v[2:5], v[44:45], off nt
	s_waitcnt vmcnt(0)
	v_pk_mul_f32 v[2:3], v[6:7], v[2:3]
	v_pk_mul_f32 v[4:5], v[8:9], v[4:5]
	v_cvt_pk_bf16_f32 v2, v2, v3
	v_cvt_pk_bf16_f32 v3, v4, v5
	global_store_dwordx2 v[62:63], v[2:3], off offset:3584
	s_cbranch_scc0 .LBB0_56
; __device__ __forceinline__ void phase0(const PT& p, LAS unsigned char* lds, int tid, int lane, int wave) {
;     ...
;     for (int m = gw; m < M; m += NGW) {
;         const f32x4* xr = (const f32x4*)(p.in[0] + (size_t)m * 2048) + lane; f32x4 v[8]; float s = 0.f;
; #pragma unroll
;         for (int j = 0; j < 8; ++j) { v[j] = xr[64 * j]; s += (v[j].x * v[j].x + v[j].y * v[j].y) + (v[j].z * v[j].z + v[j].w * v[j].w); }
;         const float rs = rsqrtf(wave_sum(s) * (1.f / 2048.f) + EPS);
;         if (lane == 0) ((float*)(ws + WS_RS0))[m] = rs;
.LBB0_54:
	s_waitcnt lgkmcnt(0)
	v_readfirstlane_b32 s15, v47
	v_readfirstlane_b32 s14, v46
	s_nop 1
	v_lshl_add_u64 v[58:59], s[14:15], 0, v[50:51]
	global_load_dwordx4 v[2:5], v[58:59], off offset:-3072 nt
	global_load_dwordx4 v[18:21], v[58:59], off offset:-4096 nt
	global_load_dwordx4 v[10:13], v[58:59], off offset:-2048 nt
	global_load_dwordx4 v[14:17], v[58:59], off offset:-1024 nt
	v_add_co_u32_e32 v60, vcc, 0xfffff000, v58
	s_waitcnt vmcnt(3)
	v_mul_f32_e32 v74, v4, v4
	v_addc_co_u32_e32 v61, vcc, -1, v59, vcc
	global_load_dwordx4 v[30:33], v[60:61], off offset:-3072 nt
	global_load_dwordx4 v[26:29], v[60:61], off offset:-2048 nt
	global_load_dwordx4 v[22:25], v[60:61], off offset:-1024 nt
	global_load_dwordx4 v[6:9], v[58:59], off nt
	s_waitcnt vmcnt(6)
	v_mul_f32_e32 v34, v19, v19
	v_mul_f32_e32 v58, v21, v21
	s_waitcnt vmcnt(5)
	v_pk_mul_f32 v[60:61], v[12:13], v[12:13]
	v_pk_mul_f32 v[62:63], v[10:11], v[10:11]
	v_mul_f32_e32 v76, v5, v5
	v_pk_fma_f32 v[68:69], v[18:19], v[18:19], v[34:35] op_sel_hi:[1,1,0]
	v_pk_fma_f32 v[58:59], v[20:21], v[20:21], v[58:59] op_sel_hi:[1,1,0]
	v_pk_mov_b32 v[70:71], v[62:63], v[60:61] op_sel:[1,0]
	v_mov_b32_e32 v63, v61
	s_waitcnt vmcnt(4)
	v_mul_f32_e32 v64, v15, v15
	v_mul_f32_e32 v66, v17, v17
	v_mov_b32_e32 v69, v74
	v_pk_add_f32 v[62:63], v[70:71], v[62:63]
	v_mov_b32_e32 v59, v76
	v_pk_fma_f32 v[60:61], v[14:15], v[14:15], v[64:65] op_sel_hi:[1,1,0]
	v_pk_fma_f32 v[64:65], v[16:17], v[16:17], v[66:67] op_sel_hi:[1,1,0]
	v_pk_add_f32 v[58:59], v[68:69], v[58:59]
	v_mul_f32_e32 v82, v2, v2
	v_mul_f32_e32 v83, v3, v3
	v_pk_add_f32 v[62:63], v[62:63], v[62:63] op_sel:[0,1] op_sel_hi:[1,0]
	s_waitcnt vmcnt(3)
	v_mov_b32_e32 v70, v31
	s_waitcnt vmcnt(2)
	v_mov_b32_e32 v71, v27
	v_mov_b32_e32 v78, v33
	v_mov_b32_e32 v79, v29
	v_mov_b32_e32 v66, v30
	v_mov_b32_e32 v67, v26
	s_waitcnt vmcnt(1)
	v_pk_mul_f32 v[72:73], v[24:25], v[24:25]
	v_pk_mul_f32 v[74:75], v[22:23], v[22:23]
	v_mov_b32_e32 v76, v32
	v_mov_b32_e32 v77, v28
	v_pk_mul_f32 v[68:69], v[70:71], v[70:71]
	v_pk_mul_f32 v[70:71], v[78:79], v[78:79]
	s_waitcnt vmcnt(0)
	v_mul_f32_e32 v61, v8, v8
	v_mul_f32_e32 v65, v9, v9
	v_pk_mov_b32 v[80:81], v[74:75], v[72:73] op_sel:[1,0]
	v_mov_b32_e32 v75, v73
	v_pk_fma_f32 v[66:67], v[66:67], v[66:67], v[68:69]
	v_pk_fma_f32 v[68:69], v[76:77], v[76:77], v[70:71]
	v_pk_add_f32 v[70:71], v[80:81], v[74:75]
	v_pk_add_f32 v[60:61], v[60:61], v[64:65]
	v_pk_add_f32 v[64:65], v[66:67], v[68:69]
	v_pk_add_f32 v[66:67], v[70:71], v[70:71] op_sel:[0,1] op_sel_hi:[1,0]
	v_pk_add_f32 v[64:65], v[64:65], v[64:65] op_sel:[0,1] op_sel_hi:[1,0]
	v_mov_b32_e32 v67, v83
	v_mov_b32_e32 v65, v82
	v_pk_add_f32 v[64:65], v[64:65], v[66:67]
	v_mul_f32_e32 v84, v7, v7
	v_pk_add_f32 v[58:59], v[64:65], v[58:59]
	v_mul_f32_e32 v85, v6, v6
	v_pk_add_f32 v[58:59], v[58:59], v[58:59] op_sel:[0,1] op_sel_hi:[1,0]
	v_mov_b32_e32 v63, v84
	v_mov_b32_e32 v59, v85
	v_pk_add_f32 v[58:59], v[58:59], v[62:63]
	s_nop 0
	v_pk_add_f32 v[58:59], v[58:59], v[60:61]
	s_nop 0
	v_add_f32_e32 v34, v58, v59
	ds_bpermute_b32 v58, v52, v34
	s_waitcnt lgkmcnt(0)
	v_add_f32_e32 v34, v34, v58
	ds_bpermute_b32 v58, v53, v34
	s_waitcnt lgkmcnt(0)
	v_add_f32_e32 v34, v34, v58
	ds_bpermute_b32 v58, v54, v34
	s_waitcnt lgkmcnt(0)
	v_add_f32_e32 v34, v34, v58
	ds_bpermute_b32 v58, v55, v34
	s_waitcnt lgkmcnt(0)
	v_add_f32_e32 v34, v34, v58
	ds_bpermute_b32 v58, v56, v34
	s_waitcnt lgkmcnt(0)
	v_add_f32_e32 v34, v34, v58
	ds_bpermute_b32 v58, v57, v34
	s_waitcnt lgkmcnt(0)
	v_add_f32_e32 v34, v34, v58
	v_fmamk_f32 v34, v34, 0x3a000000, v1
	v_mul_f32_e32 v58, 0x4b800000, v34
	v_cmp_gt_f32_e32 vcc, s7, v34
	s_nop 1
	v_cndmask_b32_e32 v34, v34, v58, vcc
	v_rsq_f32_e32 v34, v34
	s_nop 0
	v_mul_f32_e32 v58, 0x45800000, v34
	v_cndmask_b32_e32 v34, v34, v58, vcc
	s_and_saveexec_b64 s[14:15], s[0:1]
	s_cbranch_execz .LBB0_53
	s_add_u32 s20, s4, s16
	s_addc_u32 s21, s5, s17
	global_store_dword v35, v34, s[20:21]
	s_branch .LBB0_53
